# P10: one static s_setprio raise for the gather sweeps (sweeping wave issues ahead of a wave in its token prologue)
# speedup vs baseline: 1.0069x; 1.0057x over previous
; __device__ __forceinline__ void phase10(const Args& a, LAS unsigned char* lds, int tid, int wave, int lane, int vcu, int G, int emask, bool probe) {
;     ...
;     for (int rd = 0; rd < nrounds; ++rd) {
;         u32x4 hq[GTK]; float sh[GTK];
; #pragma unroll
;         for (int tk = 0; tk < GTK; ++tk) {
;             const int slot = GTK * rd + tk;
;             const size_t R = G == 256 ? ((slot < 8 || (slot == 8 && wave < 4)) ? (size_t)68 * vcu + (slot < 8 ? wave + 8 * slot : 64 + wave) : (size_t)MT) : (size_t)gw + (size_t)slot * NGW;
.LBB0_1663:
	s_setprio 0
	s_mul_i32 s60, s38, 3
	s_and_b64 vcc, exec, s[12:13]
	s_mul_i32 s53, s60, s42
	s_mul_hi_u32 s54, s60, s37
	s_mul_i32 s55, s60, s37
	s_mov_b64 s[8:9], -1
	s_cbranch_vccz .LBB0_1665
	s_add_i32 s8, s54, s53
	s_add_u32 s10, s55, s36
	s_addc_u32 s11, s8, s41
	s_mov_b64 s[8:9], 0

; __device__ __forceinline__ void phase10(const Args& a, LAS unsigned char* lds, int tid, int wave, int lane, int vcu, int G, int emask, bool probe) {
;     ...
;         u32x4 hqh[GTK][2];
; #pragma unroll
;         for (int tk = 0; tk < GTK; ++tk)
; #pragma unroll
;             for (int h = 0; h < 2; ++h)
; #pragma unroll
;                 for (int e = 0; e < 4; ++e) hqh[tk][h][e] = (unsigned)__shfl((int)hq[tk][e], 32 * h + lq);
.LBB0_1697:
	s_setprio 1
	v_add_u32_e32 v150, v67, v75
	ds_read_u16 v0, v150
	ds_read_u16 v2, v150 offset:4
	s_waitcnt lgkmcnt(13)
	ds_read_u16 v4, v150 offset:8
	s_waitcnt lgkmcnt(13)
	ds_read_u16 v5, v150 offset:12
	s_waitcnt lgkmcnt(5)
	ds_read_u16 v6, v150 offset:256
	s_waitcnt lgkmcnt(5)
	ds_read_u16 v7, v150 offset:260
	ds_read_u16 v8, v150 offset:264
	ds_read_u16 v9, v150 offset:268
	s_waitcnt lgkmcnt(7)
	v_and_b32_e32 v0, 0x3fff, v0
	v_lshlrev_b32_sdwa v68, v231, v0 dst_sel:DWORD dst_unused:UNUSED_PAD src0_sel:DWORD src1_sel:WORD_0
	s_waitcnt lgkmcnt(6)
	v_and_b32_e32 v2, 0x3fff, v2
	v_lshl_add_u64 v[0:1], v[76:77], 0, v[68:69]
	v_lshlrev_b32_sdwa v68, v231, v2 dst_sel:DWORD dst_unused:UNUSED_PAD src0_sel:DWORD src1_sel:WORD_0
	v_lshl_add_u64 v[2:3], v[76:77], 0, v[68:69]
	global_load_dwordx4 v[44:47], v[0:1], off
	global_load_dwordx4 v[36:39], v[2:3], off
	s_waitcnt lgkmcnt(5)
	v_and_b32_e32 v0, 0x3fff, v4
	v_lshlrev_b32_sdwa v68, v231, v0 dst_sel:DWORD dst_unused:UNUSED_PAD src0_sel:DWORD src1_sel:WORD_0
	s_waitcnt lgkmcnt(4)
	v_and_b32_e32 v2, 0x3fff, v5
	v_lshl_add_u64 v[0:1], v[76:77], 0, v[68:69]
	v_lshlrev_b32_sdwa v68, v231, v2 dst_sel:DWORD dst_unused:UNUSED_PAD src0_sel:DWORD src1_sel:WORD_0
	v_lshl_add_u64 v[2:3], v[76:77], 0, v[68:69]
	global_load_dwordx4 v[40:43], v[0:1], off
	global_load_dwordx4 v[32:35], v[2:3], off
	s_waitcnt lgkmcnt(3)
	v_and_b32_e32 v0, 0x3fff, v6
	v_lshlrev_b32_sdwa v68, v231, v0 dst_sel:DWORD dst_unused:UNUSED_PAD src0_sel:DWORD src1_sel:WORD_0
	s_waitcnt lgkmcnt(2)
	v_and_b32_e32 v2, 0x3fff, v7
	v_lshl_add_u64 v[0:1], v[76:77], 0, v[68:69]
	v_lshlrev_b32_sdwa v68, v231, v2 dst_sel:DWORD dst_unused:UNUSED_PAD src0_sel:DWORD src1_sel:WORD_0
	v_lshl_add_u64 v[2:3], v[76:77], 0, v[68:69]
	global_load_dwordx4 v[28:31], v[0:1], off
	global_load_dwordx4 v[16:19], v[2:3], off
	s_waitcnt lgkmcnt(1)
	v_and_b32_e32 v0, 0x3fff, v8
	v_lshlrev_b32_sdwa v68, v231, v0 dst_sel:DWORD dst_unused:UNUSED_PAD src0_sel:DWORD src1_sel:WORD_0
	s_waitcnt lgkmcnt(0)
	v_and_b32_e32 v2, 0x3fff, v9
	ds_read_u16 v4, v150 offset:512
	v_lshl_add_u64 v[0:1], v[76:77], 0, v[68:69]
	v_lshlrev_b32_sdwa v68, v231, v2 dst_sel:DWORD dst_unused:UNUSED_PAD src0_sel:DWORD src1_sel:WORD_0
	v_lshl_add_u64 v[2:3], v[76:77], 0, v[68:69]
	global_load_dwordx4 v[24:27], v[0:1], off
	global_load_dwordx4 v[12:15], v[2:3], off
	ds_read_u16 v2, v150 offset:516
	ds_read_u16 v8, v150 offset:520
	ds_read_u16 v9, v150 offset:524
	s_waitcnt lgkmcnt(3)
	v_and_b32_e32 v0, 0x3fff, v4
	v_lshlrev_b32_sdwa v68, v231, v0 dst_sel:DWORD dst_unused:UNUSED_PAD src0_sel:DWORD src1_sel:WORD_0
	s_waitcnt lgkmcnt(2)
	v_and_b32_e32 v2, 0x3fff, v2
	v_lshl_add_u64 v[0:1], v[76:77], 0, v[68:69]
	v_lshlrev_b32_sdwa v68, v231, v2 dst_sel:DWORD dst_unused:UNUSED_PAD src0_sel:DWORD src1_sel:WORD_0
	v_lshl_add_u64 v[2:3], v[76:77], 0, v[68:69]
	global_load_dwordx4 v[20:23], v[0:1], off
	global_load_dwordx4 v[4:7], v[2:3], off
	s_waitcnt lgkmcnt(1)
	v_and_b32_e32 v0, 0x3fff, v8
	v_lshlrev_b32_sdwa v68, v231, v0 dst_sel:DWORD dst_unused:UNUSED_PAD src0_sel:DWORD src1_sel:WORD_0
	s_waitcnt lgkmcnt(0)
	v_and_b32_e32 v2, 0x3fff, v9
	v_lshl_add_u64 v[0:1], v[76:77], 0, v[68:69]
	v_lshlrev_b32_sdwa v68, v231, v2 dst_sel:DWORD dst_unused:UNUSED_PAD src0_sel:DWORD src1_sel:WORD_0
	v_lshl_add_u64 v[2:3], v[76:77], 0, v[68:69]
	global_load_dwordx4 v[8:11], v[0:1], off
	s_nop 0
	global_load_dwordx4 v[0:3], v[2:3], off
	ds_bpermute_b32 v109, v221, v50
	ds_bpermute_b32 v108, v221, v48
	ds_bpermute_b32 v107, v221, v51
	ds_bpermute_b32 v106, v221, v49
	ds_bpermute_b32 v62, v222, v50
	ds_bpermute_b32 v61, v222, v51
	ds_bpermute_b32 v105, v221, v57
	ds_bpermute_b32 v104, v221, v52
	ds_bpermute_b32 v103, v221, v58
	ds_bpermute_b32 v102, v221, v53
	ds_bpermute_b32 v60, v222, v57
	ds_bpermute_b32 v59, v222, v58
	ds_bpermute_b32 v101, v221, v94
	ds_bpermute_b32 v100, v221, v63
	ds_bpermute_b32 v51, v221, v95
	ds_bpermute_b32 v50, v221, v99
	ds_bpermute_b32 v58, v222, v94
	ds_bpermute_b32 v57, v222, v95
	s_mov_b32 s34, -8
	v_mov_b32_e32 v94, v223
	v_mov_b32_e32 v95, v71
	s_branch .LBB0_1699
